# S5 mode-0 items (P2) claimed dynamically per partition as well: balances the uneven expansion-GEMM item load
# speedup vs baseline: 1.0152x; 1.0049x over previous
.LBB0_316:
	s_or_b64 exec, exec, s[0:1]
	v_add_u32_e32 v0, s71, v22
	s_lshr_b32 s25, s71, 3
	s_and_b32 s25, s25, 7
	s_lshr_b32 s24, s71, 6
	s_lshl_b32 s24, s24, 6
	s_add_i32 s24, s24, s25
	v_lshl_add_u32 v68, v22, 3, s24
	s_movk_i32 s0, 0x2100
	v_cmp_gt_i32_e32 vcc, s0, v68
	s_and_saveexec_b64 s[0:1], vcc
	s_cbranch_execz .LBB0_329
	s_movk_i32 s2, 0x4a00
	v_mul_lo_u32 v0, v22, s2
	v_add_u32_e32 v69, 0, v0
	s_lshl_b32 s14, s45, 6
	s_mov_b64 s[4:5], 0
	v_readlane_b32 s20, v253, 2
	v_readlane_b32 s21, v253, 3
	s_lshl_b32 s24, s45, 3
	s_add_i32 s24, s24, s25
	s_add_i32 s24, s24, 32
	s_lshr_b32 s22, s24, 1
	s_lshl_b32 s22, s22, 8
	s_and_b32 s23, s24, 1
	s_lshl_b32 s23, s23, 7
	s_add_i32 s22, s22, s23
	s_add_i32 s22, s22, 0xc0040
	s_add_u32 s20, s20, s22
	s_addc_u32 s21, s21, 0
	s_branch .LBB0_319
.LBB0_318:
	v_readfirstlane_b32 s24, v184
	s_add_i32 s24, s24, 0x100
	s_lshl_b32 s24, s24, 3
	s_add_i32 s24, s24, s25
	s_cmp_ge_u32 s24, 0x2100
	s_cbranch_scc1 .LBB0_329
	v_mov_b32_e32 v68, s24
.LBB0_319:
	s_mov_b64 s[22:23], exec
	s_mov_b64 exec, 1
	v_mov_b32_e32 v184, 1
	v_mov_b32_e32 v185, 0
	global_atomic_add v184, v185, v184, s[20:21] sc0
	s_mov_b64 exec, s[22:23]
	v_mul_hi_i32 v0, v68, s18
	v_lshrrev_b32_e32 v1, 31, v0
	v_ashrrev_i32_e32 v0, 5, v0
	v_add_u32_e32 v70, v0, v1
	s_movk_i32 s2, 0x84
	v_mul_lo_u32 v0, v70, s2
	v_readlane_b32 s8, v253, 0
	v_sub_u32_e32 v6, v68, v0
	v_readlane_b32 s10, v253, 2
	v_readlane_b32 s11, v253, 3
	v_lshrrev_b32_e32 v0, 5, v70
	v_mov_b32_e32 v8, v170
	s_mov_b64 s[6:7], s[10:11]
	v_lshlrev_b32_e32 v1, 6, v6
	s_movk_i32 s2, 0x2100
	v_and_b32_e32 v7, 31, v70
	v_mad_i32_i24 v2, v0, s2, v1
	v_mov_b64_e32 v[0:1], s[6:7]
	v_and_b32_e32 v9, 31, v8
	v_mad_i64_i32 v[0:1], s[2:3], v2, s97, v[0:1]
	v_lshlrev_b32_e32 v112, 5, v7
	v_lshrrev_b32_e32 v4, 2, v8
	v_lshl_add_u64 v[0:1], v[0:1], 0, v[112:113]
	s_mov_b64 s[2:3], 0x7c00000
	v_and_b32_e32 v10, 8, v4
	v_mul_u32_u24_e32 v4, 0x1c00, v9
	v_lshl_add_u64 v[0:1], v[0:1], 0, s[2:3]
	v_lshlrev_b32_e32 v4, 1, v4
	v_mov_b32_e32 v5, v113
	v_mad_u64_u32 v[2:3], s[2:3], v9, s97, v[0:1]
	v_lshlrev_b32_e32 v112, 1, v10
	v_lshl_add_u64 v[0:1], v[0:1], 0, v[4:5]
	v_lshl_add_u64 v[0:1], v[0:1], 0, v[112:113]
	s_mov_b32 s2, 0x70000
	v_lshl_add_u64 v[2:3], v[2:3], 0, v[112:113]
	v_add_co_u32_e32 v0, vcc, s2, v0
	v_readlane_b32 s9, v253, 1
	s_nop 0
	v_addc_co_u32_e32 v1, vcc, 0, v1, vcc
	global_load_dwordx4 v[16:19], v[2:3], off
	global_load_dwordx4 v[20:23], v[0:1], off
	v_and_b32_e32 v2, 63, v8
	v_lshlrev_b32_e32 v0, 4, v2
	v_mov_b32_e32 v1, v113
	v_lshl_add_u64 v[0:1], s[6:7], 0, v[0:1]
	s_mov_b64 s[8:9], 0x80000
	v_lshl_add_u64 v[58:59], v[0:1], 0, s[8:9]
	v_lshlrev_b32_e32 v0, 5, v9
	v_mov_b32_e32 v1, v113
	v_lshl_add_u64 v[0:1], s[6:7], 0, v[0:1]
	v_lshl_add_u64 v[0:1], v[0:1], 0, v[112:113]
	s_mov_b64 s[8:9], 0x100000
	v_lshlrev_b32_e32 v112, 2, v2
	v_lshl_add_u64 v[60:61], v[0:1], 0, s[8:9]
	v_lshl_add_u64 v[0:1], s[6:7], 0, v[112:113]
	s_mov_b64 s[6:7], 0x19e00000
	s_movk_i32 s2, 0x80
	v_lshl_add_u64 v[62:63], v[0:1], 0, s[6:7]
	v_add_u32_e32 v0, v69, v10
	s_movk_i32 s6, 0x50
	v_mul_u32_u24_e32 v1, 0x50, v9
	v_cmp_gt_i32_e64 s[2:3], s2, v6
	s_mov_b32 s15, 0
	v_mad_u32_u24 v71, v2, s6, v69
	v_sub_u32_e32 v72, 0x83, v6
	v_add_u32_e32 v73, 0xffffff80, v6
	v_add_u32_e32 v74, 4, v6
	v_or_b32_e32 v75, s14, v7
	s_mov_b64 s[6:7], -1
	v_add_u32_e32 v76, v0, v1
	s_branch .LBB0_321
